# attention loop: static s_setprio 1 for waves 4-7 (on top of v11)
# speedup vs baseline: 1.0033x; 1.0033x over previous
; __device__ __forceinline__ void attn_body(const bf16_t* __restrict__ Qb, const bf16_t* __restrict__ KVb, int hcol, bf16_t* __restrict__ Ob, float* __restrict__ rsqa, int seq, char* lds) {
;   int tid_ = threadIdx.x; asm volatile("" : "+v"(tid_));
;   const int tid = tid_, wid = __builtin_amdgcn_readfirstlane(tid >> 6), lane = tid & 63, r32 = lane & 31, hi = lane >> 5;
;   char* V_lds = lds; char* K_lds = lds + 2 * SHM_V;
;   float* ws = (float*)(lds + 2 * SHM_V + 3 * SHM_K) + wid * 64; float* li_l = ws; float* al_l = ws + 32;
;   float m_reg = -1e30f, l_reg = 0; f32x16 o[4] = {}; bf16x8 qr[8];
;   char* qlds = lds + 2 * SHM_V + 3 * SHM_K + NW * 64 * 4 + wid * 4096 + lane * 16;
;   int kb[4];
; #pragma unroll
;   for (int dl = 0; dl < 4; ++dl) kb[dl] = r32 * 384 + ((dl * 32 + hi * 16) ^ (((r32 >> 1) & 7) << 4));
;   const bf16_t* Qw = Qb + (long)(wid * QBLK + r32) * LDQ + hi * 8;
; #pragma unroll
;   for (int d0 = 0; d0 < 8; ++d0) qr[d0] = *reinterpret_cast<const bf16x8*>(Qw + d0 * 16);
; #pragma unroll
;   for (int d0 = 8; d0 < 12; ++d0) *reinterpret_cast<bf16x8*>(qlds + (d0 - 8) * 1024) = *reinterpret_cast<const bf16x8*>(Qw + d0 * 16);
;   DmaCtx dc; dc.wid = wid; dc.srd = __builtin_amdgcn_make_buffer_rsrc((void*)KVb, (short)0, 0x7fffffff, 0x00020000);
; #pragma unroll
;   for (int i = 0; i < 3; ++i) { const int b = (wid + 8 * i) * 1024 + lane * 16, row = b / 384, x = b % 384, blk = x >> 7, ch = ((x & 127) >> 4) ^ ((row >> 1) & 7), col = blk * 64 + ch * 8;
;     dc.koff[i] = (unsigned)(row * LDKV + (col < 128 ? hcol + col : 2048 + (col - 128))) * 2u; }
; #pragma unroll
;   for (int i = 0; i < 2; ++i) { const int b = (wid + 8 * i) * 1024 + lane * 16, st_ = b >> 9, kk = (st_ >> 2) * 8 + ((b & 511) >> 6), c = (st_ & 3) * 32 + ((b & 63) >> 1);
;     const int k = (kk & ~0xC) | ((kk & 4) << 1) | ((kk & 8) >> 1);
;     dc.voff[i] = (unsigned)(k * LDKV + hcol + 128 + c) * 2u; }
;   const __attribute__((address_space(3))) char* vb0 = (const __attribute__((address_space(3))) char*)V_lds + v_rd_base(lane);
;   constexpr size_t TILEB = (size_t)KVBLK * LDKV * 2;
;     ...
;   f32x16 pA0, pA1, pB0, pB1; float alA, alB; bf16x8 pa0, pa1, pa2, pa3; SMState st; const int NT = seq / KVBLK;
;   DMAK(0, 0); DMAV(0, 0); DMAK(1, 1);
;   asm volatile("s_waitcnt vmcnt(3)" ::: "memory"); BAR();
.LBB0_654:
	s_lshl_b32 s36, s0, 8
	s_add_i32 s8, s6, s36
	s_ashr_i32 s9, s8, 31
	s_mul_i32 s1, s8, 0xc00
	s_mul_hi_i32 s0, s8, 0xc00
	s_add_u32 s4, s3, s1
	s_addc_u32 s5, s21, s0
	s_ashr_i32 s7, s6, 31
	s_mul_i32 s1, s6, 0x1080
	v_mov_b32_e32 v72, v168
	s_mul_hi_i32 s0, s6, 0x1080
	s_add_u32 s28, s20, s1
	s_addc_u32 s10, s87, s0
	v_readfirstlane_b32 s1, v72
	s_ashr_i32 s11, s1, 6
	v_and_b32_e32 v187, 31, v72
	s_lshl_b32 s0, s11, 5
	v_bfe_u32 v186, v72, 5, 1
	v_or_b32_e32 v2, s0, v187
	v_mov_b64_e32 v[0:1], s[4:5]
	v_lshlrev_b32_e32 v166, 4, v186
	v_mad_i64_i32 v[0:1], s[4:5], v2, s42, v[0:1]
	v_lshl_add_u64 v[16:17], v[0:1], 0, v[166:167]
	global_load_dwordx4 v[0:3], v[16:17], off offset:256
	global_load_dwordx4 v[4:7], v[16:17], off offset:288
	global_load_dwordx4 v[8:11], v[16:17], off offset:320
	global_load_dwordx4 v[12:15], v[16:17], off offset:352
	global_load_dwordx4 v[156:159], v[16:17], off
	global_load_dwordx4 v[152:155], v[16:17], off offset:32
	global_load_dwordx4 v[148:151], v[16:17], off offset:64
	global_load_dwordx4 v[144:147], v[16:17], off offset:96
	global_load_dwordx4 v[140:143], v[16:17], off offset:128
	global_load_dwordx4 v[136:139], v[16:17], off offset:160
	global_load_dwordx4 v[132:135], v[16:17], off offset:192
	global_load_dwordx4 v[128:131], v[16:17], off offset:224
	v_and_b32_e32 v96, 63, v72
	v_lshlrev_b32_e32 v18, 3, v72
	v_lshlrev_b32_e32 v73, 4, v96
	s_lshl_b32 s69, s11, 10
	v_and_b32_e32 v57, 0x70, v18
	s_lshl_b32 s4, s11, 12
	v_or_b32_e32 v18, s69, v73
	s_add_i32 s4, s4, 0
	v_mul_hi_i32 v19, v18, s43
	v_add_u32_e32 v20, 0x2000, v18
	s_add_i32 s4, s4, 0x1a800
	v_add_u32_e32 v21, 0x4000, v18
	v_lshrrev_b32_e32 v22, 31, v19
	v_ashrrev_i32_e32 v19, 6, v19
	v_mul_hi_i32 v23, v20, s43
	v_add_u32_e32 v192, s4, v73
	v_mul_hi_i32 v24, v21, s43
	v_add_u32_e32 v16, v19, v22
	v_lshrrev_b32_e32 v17, 31, v23
	v_ashrrev_i32_e32 v19, 6, v23
	v_lshrrev_b32_e32 v22, 31, v24
	v_mul_i32_i24_e32 v23, 0x180, v16
	v_add_u32_e32 v17, v19, v17
	v_sub_u32_e32 v18, v18, v23
	v_mul_i32_i24_e32 v19, 0x180, v17
	v_lshrrev_b32_e32 v25, 1, v16
	v_lshrrev_b32_e32 v26, 4, v18
	v_sub_u32_e32 v19, v20, v19
	v_lshrrev_b32_e32 v23, 1, v17
	v_ashrrev_i32_e32 v18, 1, v18
	v_xor_b32_e32 v20, v26, v25
	v_lshrrev_b32_e32 v25, 4, v19
	v_and_b32_e32 v18, 0xffffffc0, v18
	v_ashrrev_i32_e32 v19, 1, v19
	v_lshlrev_b32_e32 v20, 3, v20
	v_xor_b32_e32 v23, v25, v23
	v_and_b32_e32 v19, 0xffffffc0, v19
	v_and_or_b32 v18, v20, 56, v18
	v_lshlrev_b32_e32 v20, 3, v23
	v_cmp_gt_i32_e32 vcc, s40, v18
	v_mad_i32_i24 v16, v16, s44, v18
	v_and_or_b32 v18, v20, 56, v19
	v_cndmask_b32_e32 v23, v161, v163, vcc
	v_cmp_gt_i32_e32 vcc, s40, v18
	s_and_b32 s4, s1, 64
	v_add_lshl_u32 v194, v16, v23, 1
	v_cndmask_b32_e32 v16, v161, v163, vcc
	s_and_b32 s29, s10, 0xffff
	s_add_i32 s70, s69, 0
	v_mad_i32_i24 v17, v17, s44, v18
	v_lshlrev_b32_e32 v74, 3, v96
	s_add_i32 m0, s70, 0x8000
	v_add_lshl_u32 v195, v17, v16, 1
	v_and_b32_e32 v75, 24, v74
	s_add_i32 s71, s70, 0x2000
	v_mul_u32_u24_e32 v56, 0x180, v187
	v_bitop3_b32 v193, v166, v56, v57 bitop3:0xde
	v_add_u32_e32 v68, 0, v193
	v_or_b32_e32 v48, 64, v166
	v_bitop3_b32 v200, v48, v56, v57 bitop3:0xde
	v_add_u32_e32 v70, 0, v200
	v_or_b32_e32 v58, 0x60, v166
	v_bitop3_b32 v201, v58, v56, v57 bitop3:0xde
	v_add_u32_e32 v71, 0, v201
	s_waitcnt vmcnt(11)
	ds_write_b128 v192, v[0:3]
	s_waitcnt vmcnt(10)
	ds_write_b128 v192, v[4:7] offset:1024
	s_waitcnt vmcnt(9)
	ds_write_b128 v192, v[8:11] offset:2048
	s_waitcnt vmcnt(8)
	ds_write_b128 v192, v[12:15] offset:3072
	v_ashrrev_i32_e32 v0, 6, v24
	v_add_u32_e32 v0, v0, v22
	v_mul_i32_i24_e32 v1, 0x180, v0
	v_sub_u32_e32 v1, v21, v1
	v_lshrrev_b32_e32 v2, 4, v1
	v_lshrrev_b32_e32 v3, 1, v0
	v_xor_b32_e32 v2, v2, v3
	v_ashrrev_i32_e32 v1, 1, v1
	v_and_b32_e32 v1, 0xffffffc0, v1
	v_lshlrev_b32_e32 v2, 3, v2
	v_and_or_b32 v1, v2, 56, v1
	v_cmp_gt_i32_e32 vcc, s40, v1
	v_mad_i32_i24 v0, v0, s44, v1
	v_bitop3_b32 v1, s4, v165, v96 bitop3:0xc8
	s_ashr_i32 s4, s69, 8
	v_cndmask_b32_e32 v2, v161, v163, vcc
	s_and_b32 s5, s4, 0x3fffff0
	s_lshr_b32 s4, s4, 1
	v_add_lshl_u32 v196, v0, v2, 1
	v_bfe_u32 v0, v72, 2, 2
	v_lshrrev_b32_e32 v2, 1, v72
	s_and_b32 s4, s4, 4
	v_and_or_b32 v0, v2, 8, v0
	s_or_b32 s4, s5, s4
	v_or_b32_e32 v2, s4, v0
	s_add_i32 s4, s69, 0x2000
	s_ashr_i32 s5, s4, 8
	s_and_b32 s10, s5, 0x3fffff0
	s_lshr_b32 s5, s5, 1
	s_and_b32 s5, s5, 4
	s_or_b32 s5, s10, s5
	buffer_load_dwordx4 v194, s[28:31], 0 offen lds
	s_add_i32 m0, s70, 0xa000
	v_or3_b32 v1, v1, s41, v75
	v_mul_lo_u32 v2, v2, s44
	v_or_b32_e32 v0, s5, v0
	buffer_load_dwordx4 v195, s[28:31], 0 offen lds
	s_add_i32 m0, s70, 0xc000
	v_add_lshl_u32 v197, v1, v2, 1
	v_mul_lo_u32 v0, v0, s44
	buffer_load_dwordx4 v196, s[28:31], 0 offen lds
	s_mov_b32 m0, s70
	v_add_lshl_u32 v198, v0, v1, 1
	buffer_load_dwordx4 v197, s[28:31], 0 offen lds
	s_mov_b32 m0, s71
	s_add_i32 s5, s69, s45
	buffer_load_dwordx4 v198, s[28:31], 0 offen lds
	s_add_i32 m0, s70, 0xe000
	v_or_b32_e32 v8, 32, v166
	buffer_load_dwordx4 v194, s[28:31], s66 offen lds
	s_add_i32 m0, s45, s4
	v_bitop3_b32 v199, v8, v56, v57 bitop3:0xde
	buffer_load_dwordx4 v195, s[28:31], s66 offen lds
	s_add_i32 m0, s5, 0x4000
	v_add_u32_e32 v69, 0, v199
	buffer_load_dwordx4 v196, s[28:31], s66 offen lds
	s_waitcnt vmcnt(3)
	s_waitcnt lgkmcnt(0)
	s_barrier
; #define DMAK(t, s) do { dc.gk = (unsigned)((size_t)(t) * TILEB); dc.kd = K_lds + (s) * SHM_K; dma_piece<0>(dc); dma_piece<1>(dc); dma_piece<2>(dc); } while (0)
; #define DMAV(t, s) do { dc.gv = (unsigned)((size_t)(t) * TILEB); dc.vd = V_lds + (s) * SHM_V; dma_piece<3>(dc); dma_piece<4>(dc); } while (0)
; #define BAR() do { asm volatile("s_waitcnt lgkmcnt(0)" ::: "memory"); __builtin_amdgcn_s_barrier(); asm volatile("" ::: "memory"); } while (0)
; __device__ __forceinline__ void qkt(f32x16& p0, f32x16& p1, const char* Ks, const bf16x8* qr, const char* qlds, const int* kb) {
;   p0 = f32x16{}; p1 = f32x16{};
; #pragma unroll
;   for (int d0 = 0; d0 < 12; ++d0) { const int off = kb[d0 & 3] + (d0 >> 2) * 128;
;     bf16x8 b0 = *reinterpret_cast<const bf16x8*>(Ks + off);
;     bf16x8 b1 = *reinterpret_cast<const bf16x8*>(Ks + off + 32 * 384);
;     bf16x8 q; if (d0 < 8) q = qr[d0]; else q = *reinterpret_cast<const bf16x8*>(qlds + (d0 - 8) * 1024);
;     p0 = __builtin_amdgcn_mfma_f32_32x32x16_bf16(b0, q, p0, 0, 0, 0);
;     p1 = __builtin_amdgcn_mfma_f32_32x32x16_bf16(b1, q, p1, 0, 0, 0); }
; }
; __device__ __forceinline__ void attn_body(const bf16_t* __restrict__ Qb, const bf16_t* __restrict__ KVb, int hcol, bf16_t* __restrict__ Ob, float* __restrict__ rsqa, int seq, char* lds) {
;     ...
;   DMAK(0, 0); DMAV(0, 0); DMAK(1, 1);
;   asm volatile("s_waitcnt vmcnt(3)" ::: "memory"); BAR();
;   qkt(pA0, pA1, K_lds, qr, qlds, kb); partialSM0(pA0, pA1, m_reg); alA = 1.f;
;   asm volatile("s_waitcnt vmcnt(0)" ::: "memory"); BAR();
	ds_read_b128 v[0:3], v68 offset:32768
	ds_read_b128 v[4:7], v68 offset:32896
	s_waitcnt vmcnt(15) lgkmcnt(1)
	v_mfma_f32_32x32x16_bf16 v[16:31], v[0:3], v[156:159], 0
	ds_read_b128 v[0:3], v68 offset:45056
	ds_read_b128 v[8:11], v68 offset:33024
	s_and_b32 s1, s1, 0x3fffffc0
	s_mov_b32 s49, s48
	s_lshl_b32 s1, s1, 2
	s_mov_b32 s50, s48
	s_mov_b32 s51, s48
	s_waitcnt lgkmcnt(1)
	v_mfma_f32_32x32x16_bf16 v[32:47], v[0:3], v[156:159], 0
	ds_read_b128 v[0:3], v69 offset:32768
	ds_read_b128 v[12:15], v69 offset:32896
	ds_read_b128 v[48:51], v69 offset:33024
	s_mov_b32 s52, s48
	s_mov_b32 s53, s48
	s_mov_b32 s54, s48
	s_mov_b32 s55, s48
	s_mov_b32 s56, s48
	s_waitcnt vmcnt(14) lgkmcnt(2)
	v_mfma_f32_32x32x16_bf16 v[16:31], v[0:3], v[152:155], v[16:31]
	ds_read_b128 v[0:3], v69 offset:45056
	s_mov_b32 s57, s48
	s_mov_b32 s58, s48
	s_mov_b32 s59, s48
	s_mov_b32 s60, s48
	s_mov_b32 s61, s48
	s_mov_b32 s62, s48
	s_waitcnt lgkmcnt(0)
	v_mfma_f32_32x32x16_bf16 v[32:47], v[0:3], v[152:155], v[32:47]
	ds_read_b128 v[0:3], v70 offset:32768
	ds_read_b128 v[52:55], v70 offset:32896
	ds_read_b128 v[56:59], v70 offset:33024
	s_mov_b32 s63, s48
	s_add_i32 s1, s1, 0
	s_add_i32 s1, s1, 0x1a000
	s_mov_b32 s72, 2
	s_mov_b32 s73, 1
	s_waitcnt vmcnt(13) lgkmcnt(2)
	v_mfma_f32_32x32x16_bf16 v[16:31], v[0:3], v[148:151], v[16:31]
	ds_read_b128 v[0:3], v70 offset:45056
	v_cmp_gt_u32_e64 s[4:5], 32, v96
	v_lshl_add_u32 v189, v187, 2, s1
	v_mov_b32_e32 v202, 1.0
	v_mov_b32_e32 v190, 0
	s_waitcnt lgkmcnt(0)
	v_mfma_f32_32x32x16_bf16 v[32:47], v[0:3], v[148:151], v[32:47]
	ds_read_b128 v[0:3], v71 offset:32768
	ds_read_b128 v[60:63], v71 offset:32896
	s_waitcnt vmcnt(12) lgkmcnt(1)
	v_mfma_f32_32x32x16_bf16 v[16:31], v[0:3], v[144:147], v[16:31]
	ds_read_b128 v[0:3], v71 offset:45056
	ds_read_b128 v[64:67], v71 offset:33024
	s_waitcnt lgkmcnt(1)
	v_mfma_f32_32x32x16_bf16 v[32:47], v[0:3], v[144:147], v[32:47]
	s_waitcnt vmcnt(11)
	v_mfma_f32_32x32x16_bf16 v[16:31], v[4:7], v[140:143], v[16:31]
	ds_read_b128 v[0:3], v68 offset:45184
	ds_read_b128 v[4:7], v68 offset:45312
	s_waitcnt lgkmcnt(1)
	v_mfma_f32_32x32x16_bf16 v[32:47], v[0:3], v[140:143], v[32:47]
	s_waitcnt vmcnt(10)
	v_mfma_f32_32x32x16_bf16 v[16:31], v[12:15], v[136:139], v[16:31]
	ds_read_b128 v[0:3], v69 offset:45184
	ds_read_b128 v[12:15], v69 offset:45312
	s_waitcnt lgkmcnt(1)
	v_mfma_f32_32x32x16_bf16 v[32:47], v[0:3], v[136:139], v[32:47]
	s_waitcnt vmcnt(9)
	v_mfma_f32_32x32x16_bf16 v[16:31], v[52:55], v[132:135], v[16:31]
	ds_read_b128 v[0:3], v70 offset:45184
	ds_read_b128 v[52:55], v70 offset:45312
	s_waitcnt lgkmcnt(1)
	v_mfma_f32_32x32x16_bf16 v[32:47], v[0:3], v[132:135], v[32:47]
	s_waitcnt vmcnt(8)
	v_mfma_f32_32x32x16_bf16 v[16:31], v[60:63], v[128:131], v[16:31]
	ds_read_b128 v[0:3], v71 offset:45184
	ds_read_b128 v[60:63], v71 offset:45312
	s_waitcnt lgkmcnt(1)
	v_mfma_f32_32x32x16_bf16 v[32:47], v[0:3], v[128:131], v[32:47]
	ds_read_b128 v[0:3], v192
	ds_read_b128 v[68:71], v192 offset:1024
	s_waitcnt lgkmcnt(1)
	v_mfma_f32_32x32x16_bf16 v[16:31], v[8:11], v[0:3], v[16:31]
	v_mfma_f32_32x32x16_bf16 v[32:47], v[4:7], v[0:3], v[32:47]
	ds_read_b128 v[0:3], v192 offset:2048
	v_lshlrev_b32_e32 v5, 1, v72
	v_and_b32_e32 v4, 0xc0, v73
	v_and_b32_e32 v6, 0x100, v74
	v_add3_u32 v4, 0, v75, v4
	v_and_b32_e32 v5, 32, v5
	v_add3_u32 v188, v4, v5, v6
	s_waitcnt lgkmcnt(1)
	v_mfma_f32_32x32x16_bf16 v[16:31], v[48:51], v[68:71], v[16:31]
	ds_read_b128 v[48:51], v192 offset:3072
	s_waitcnt vmcnt(0)
	s_waitcnt lgkmcnt(0)
	s_barrier
; #define BAR() do { asm volatile("s_waitcnt lgkmcnt(0)" ::: "memory"); __builtin_amdgcn_s_barrier(); asm volatile("" ::: "memory"); } while (0)
; __device__ __forceinline__ void partialSM0(f32x16& p0, f32x16& p1, float& M) {
;   float pmax = p0[0];
; #pragma unroll
;   for (int r = 1; r < 16; ++r) pmax = fmaxf(pmax, p0[r]);
; #pragma unroll
;   for (int r = 0; r < 16; ++r) pmax = fmaxf(pmax, p1[r]);
;   { auto rr = __builtin_amdgcn_permlane32_swap(__float_as_uint(pmax), __float_as_uint(pmax), false, false);
;     pmax = fmaxf(__uint_as_float(rr[0]), __uint_as_float(rr[1])); }
;   M = pmax;
; #pragma unroll
;   for (int r = 0; r < 16; ++r) { p0[r] -= pmax; p1[r] -= pmax; }
; #pragma unroll
;   for (int r = 0; r < 16; ++r) p0[r] = __builtin_amdgcn_exp2f(p0[r]);
; }
; __device__ __forceinline__ void attn_body(const bf16_t* __restrict__ Qb, const bf16_t* __restrict__ KVb, int hcol, bf16_t* __restrict__ Ob, float* __restrict__ rsqa, int seq, char* lds) {
;     ...
;   qkt(pA0, pA1, K_lds, qr, qlds, kb); partialSM0(pA0, pA1, m_reg); alA = 1.f;
;   asm volatile("s_waitcnt vmcnt(0)" ::: "memory"); BAR();
;   int sc = 1;
;   for (int j = 1; j + 1 < NT; j += 2) {
;     STEP(pB0, pB1, alB, pA0, pA1, alA, j, sc, 0);
	v_mfma_f32_32x32x16_bf16 v[32:47], v[12:15], v[68:71], v[32:47]
	s_waitcnt lgkmcnt(1)
	v_mfma_f32_32x32x16_bf16 v[16:31], v[56:59], v[0:3], v[16:31]
	v_mfma_f32_32x32x16_bf16 v[32:47], v[52:55], v[0:3], v[32:47]
	v_mov_b64_e32 v[0:1], s[48:49]
	v_mov_b64_e32 v[14:15], s[62:63]
	v_mov_b64_e32 v[2:3], s[50:51]
	v_mov_b64_e32 v[4:5], s[52:53]
	v_mov_b64_e32 v[6:7], s[54:55]
	v_mov_b64_e32 v[8:9], s[56:57]
	v_mov_b64_e32 v[10:11], s[58:59]
	s_waitcnt lgkmcnt(0)
	v_mfma_f32_32x32x16_bf16 v[16:31], v[64:67], v[48:51], v[16:31]
	v_mov_b64_e32 v[12:13], s[60:61]
	s_add_i32 s50, s70, 0x4000
	s_add_i32 s49, s70, 0x6000
	s_mov_b32 s51, 0x84000
	v_mfma_f32_32x32x16_bf16 v[32:47], v[60:63], v[48:51], v[32:47]
	s_nop 6
	v_max_f32_e32 v48, v17, v17
	v_max_f32_e32 v49, v16, v16
	v_max_f32_e32 v48, v49, v48
	v_max3_f32 v48, v48, v18, v19
	v_max3_f32 v48, v48, v20, v21
	v_max3_f32 v48, v48, v22, v23
	v_max3_f32 v48, v48, v24, v25
	v_max3_f32 v48, v48, v26, v27
	v_max3_f32 v48, v48, v28, v29
	v_max3_f32 v48, v48, v30, v31
	v_max3_f32 v48, v48, v32, v33
	v_max3_f32 v48, v48, v34, v35
	v_max3_f32 v48, v48, v36, v37
	v_max3_f32 v48, v48, v38, v39
	v_max3_f32 v48, v48, v40, v41
	v_max3_f32 v48, v48, v42, v43
	v_max3_f32 v48, v48, v44, v45
	v_max3_f32 v48, v48, v46, v47
	v_mov_b32_e32 v49, v48
	s_nop 1
	v_permlane32_swap_b32_e32 v48, v49
	v_max_f32_e32 v49, v49, v49
	v_max_f32_e32 v48, v48, v48
	v_max_f32_e32 v191, v48, v49
	v_sub_f32_e32 v16, v16, v191
	v_exp_f32_e32 v64, v16
	v_sub_f32_e32 v16, v17, v191
	v_exp_f32_e32 v65, v16
	v_sub_f32_e32 v16, v18, v191
	v_exp_f32_e32 v66, v16
	v_sub_f32_e32 v16, v19, v191
	v_exp_f32_e32 v67, v16
	v_sub_f32_e32 v16, v20, v191
	v_exp_f32_e32 v68, v16
	v_sub_f32_e32 v16, v21, v191
	v_exp_f32_e32 v69, v16
	v_sub_f32_e32 v16, v22, v191
	v_exp_f32_e32 v70, v16
	v_sub_f32_e32 v16, v23, v191
	v_exp_f32_e32 v71, v16
	v_sub_f32_e32 v16, v24, v191
	v_exp_f32_e32 v72, v16
	v_sub_f32_e32 v16, v25, v191
	v_exp_f32_e32 v73, v16
	v_sub_f32_e32 v16, v26, v191
	v_exp_f32_e32 v74, v16
	v_sub_f32_e32 v16, v27, v191
	v_exp_f32_e32 v75, v16
	v_sub_f32_e32 v16, v28, v191
	v_exp_f32_e32 v76, v16
	v_sub_f32_e32 v16, v29, v191
	v_exp_f32_e32 v77, v16
	v_sub_f32_e32 v16, v30, v191
	v_exp_f32_e32 v78, v16
	v_sub_f32_e32 v16, v31, v191
	v_exp_f32_e32 v79, v16
	v_sub_f32_e32 v95, v47, v191
	v_sub_f32_e32 v94, v46, v191
	v_sub_f32_e32 v93, v45, v191
	v_sub_f32_e32 v92, v44, v191
	v_sub_f32_e32 v91, v43, v191
	v_sub_f32_e32 v90, v42, v191
	v_sub_f32_e32 v89, v41, v191
	v_sub_f32_e32 v88, v40, v191
	v_sub_f32_e32 v87, v39, v191
	v_sub_f32_e32 v86, v38, v191
	v_sub_f32_e32 v85, v37, v191
	v_sub_f32_e32 v84, v36, v191
	v_sub_f32_e32 v83, v35, v191
	v_sub_f32_e32 v82, v34, v191
	v_sub_f32_e32 v81, v33, v191
	v_sub_f32_e32 v80, v32, v191
	v_mov_b64_e32 v[62:63], v[14:15]
	v_mov_b64_e32 v[46:47], v[14:15]
	v_mov_b64_e32 v[30:31], v[14:15]
	v_mov_b64_e32 v[60:61], v[12:13]
	v_mov_b64_e32 v[58:59], v[10:11]
	v_mov_b64_e32 v[56:57], v[8:9]
	v_mov_b64_e32 v[54:55], v[6:7]
	v_mov_b64_e32 v[52:53], v[4:5]
	v_mov_b64_e32 v[50:51], v[2:3]
	v_mov_b64_e32 v[48:49], v[0:1]
	v_mov_b64_e32 v[44:45], v[12:13]
	v_mov_b64_e32 v[42:43], v[10:11]
	v_mov_b64_e32 v[40:41], v[8:9]
	v_mov_b64_e32 v[38:39], v[6:7]
	v_mov_b64_e32 v[36:37], v[4:5]
	v_mov_b64_e32 v[34:35], v[2:3]
	v_mov_b64_e32 v[32:33], v[0:1]
	v_mov_b64_e32 v[28:29], v[12:13]
	v_mov_b64_e32 v[26:27], v[10:11]
	v_mov_b64_e32 v[24:25], v[8:9]
	v_mov_b64_e32 v[22:23], v[6:7]
	v_mov_b64_e32 v[20:21], v[4:5]
	v_mov_b64_e32 v[18:19], v[2:3]
	v_mov_b64_e32 v[16:17], v[0:1]
	s_cmp_lt_u32 s69, 0x1000
	s_cbranch_scc1 .Lattn_prio
	s_setprio 1
.Lattn_prio:
.LBB0_655:
	s_add_i32 s10, s73, 1
	s_cmp_lg_u32 s73, 2
	s_cselect_b32 s52, s10, 0
	s_mul_i32 s10, s73, 0x6000
	v_add_u32_e32 v203, s10, v193
	ds_read_b128 v[204:207], v203 offset:32768
	ds_read_b128 v[208:211], v203 offset:45056

; #define SBAR() __builtin_amdgcn_sched_barrier(0)
; #define DMAV(t, s) do { dc.gv = (unsigned)((size_t)(t) * TILEB); dc.vd = V_lds + (s) * SHM_V; dma_piece<3>(dc); dma_piece<4>(dc); } while (0)
; __device__ __forceinline__ void finishSM(f32x16& p0, f32x16& p1, float alpha, float& l_reg, bf16x8& pa0, bf16x8& pa1, bf16x8& pa2, bf16x8& pa3) {
; #pragma unroll
;   for (int r = 0; r < 16; ++r) p1[r] = __builtin_amdgcn_exp2f(p1[r]);
;   float ps = 0;
; #pragma unroll
;   for (int r = 0; r < 16; ++r) ps += p0[r];
; #pragma unroll
;   for (int r = 0; r < 16; ++r) ps += p1[r];
;   { auto rr = __builtin_amdgcn_permlane32_swap(__float_as_uint(ps), __float_as_uint(ps), false, false);
;     ps = __uint_as_float(rr[0]) + __uint_as_float(rr[1]); }
;   l_reg = l_reg * alpha + ps;
;     ...
;   PK4(p0, 0, pa0); PK4(p0, 8, pa1); PK4(p1, 0, pa2); PK4(p1, 8, pa3);
;     ...
; }
; __device__ __forceinline__ void qkt(f32x16& p0, f32x16& p1, const char* Ks, const bf16x8* qr, const char* qlds, const int* kb) {
;   p0 = f32x16{}; p1 = f32x16{};
; #pragma unroll
;   for (int d0 = 0; d0 < 12; ++d0) { const int off = kb[d0 & 3] + (d0 >> 2) * 128;
;     bf16x8 b0 = *reinterpret_cast<const bf16x8*>(Ks + off);
;     bf16x8 b1 = *reinterpret_cast<const bf16x8*>(Ks + off + 32 * 384);
;     bf16x8 q; if (d0 < 8) q = qr[d0]; else q = *reinterpret_cast<const bf16x8*>(qlds + (d0 - 8) * 1024);
;     p0 = __builtin_amdgcn_mfma_f32_32x32x16_bf16(b0, q, p0, 0, 0, 0);
;     p1 = __builtin_amdgcn_mfma_f32_32x32x16_bf16(b1, q, p1, 0, 0, 0); }
; }
; __device__ __forceinline__ void attn_body(const bf16_t* __restrict__ Qb, const bf16_t* __restrict__ KVb, int hcol, bf16_t* __restrict__ Ob, float* __restrict__ rsqa, int seq, char* lds) {
;     ...
;   DMAV(NT - 1, 1);
;   SBAR(); qkt(pB0, pB1, K_lds + sc * SHM_K, qr, qlds, kb);
;   finishSM(pA0, pA1, alA, l_reg, pa0, pa1, pa2, pa3);
.LBB0_670:
	s_setprio 0
	s_mul_i32 s10, s37, 0x42000
	s_add_i32 s10, s10, 0xfffbe000
	s_mov_b32 m0, s50
	s_nop 0
	buffer_load_dwordx4 v197, s[28:31], s10 offen lds
	s_mov_b32 m0, s49
	s_nop 0
	buffer_load_dwordx4 v198, s[28:31], s10 offen lds
	v_add_u32_e32 v193, s52, v193
	ds_read_b128 v[96:99], v193 offset:32768
	ds_read_b128 v[194:197], v193 offset:32896
	ds_read_b128 v[112:115], v193 offset:45056
	ds_read_b128 v[206:209], v193 offset:33024
	v_add_u32_e32 v202, s52, v199
	v_add_u32_e32 v203, s52, v200
	s_waitcnt lgkmcnt(3)
	v_mfma_f32_32x32x16_bf16 v[96:111], v[96:99], v[156:159], 0
	v_add_u32_e32 v204, s52, v201
	v_exp_f32_e32 v222, v83
	v_cvt_pk_bf16_f32 v83, v70, v71
	v_exp_f32_e32 v223, v84
	v_cvt_pk_bf16_f32 v84, v72, v73
	v_exp_f32_e32 v224, v89
	v_exp_f32_e32 v225, v90
	s_waitcnt lgkmcnt(1)
	v_mfma_f32_32x32x16_bf16 v[112:127], v[112:115], v[156:159], 0
	ds_read_b128 v[156:159], v202 offset:32768
	ds_read_b128 v[210:213], v202 offset:32896
	v_exp_f32_e32 v226, v91
	v_exp_f32_e32 v227, v92
	v_exp_f32_e32 v228, v93
	v_exp_f32_e32 v229, v94
	v_exp_f32_e32 v230, v95
	v_cvt_pk_bf16_f32 v93, v225, v226
	s_waitcnt lgkmcnt(1)
	v_mfma_f32_32x32x16_bf16 v[96:111], v[156:159], v[152:155], v[96:111]
	ds_read_b128 v[156:159], v202 offset:45056
	ds_read_b128 v[214:217], v202 offset:33024
	v_cvt_pk_bf16_f32 v94, v227, v228
	v_cvt_pk_bf16_f32 v95, v229, v230
	s_nop 1
	v_permlane32_swap_b32_e32 v93, v95
	s_waitcnt lgkmcnt(1)
	v_mfma_f32_32x32x16_bf16 v[112:127], v[156:159], v[152:155], v[112:127]
	ds_read_b128 v[152:155], v203 offset:32768
	ds_read_b128 v[156:159], v203 offset:32896
	s_waitcnt lgkmcnt(1)
	v_mfma_f32_32x32x16_bf16 v[96:111], v[152:155], v[148:151], v[96:111]
	ds_read_b128 v[152:155], v203 offset:45056
	ds_read_b128 v[218:221], v203 offset:33024
	s_waitcnt lgkmcnt(1)
	v_mfma_f32_32x32x16_bf16 v[112:127], v[152:155], v[148:151], v[112:127]
	ds_read_b128 v[148:151], v204 offset:32768
	ds_read_b128 v[152:155], v204 offset:32896
	s_waitcnt lgkmcnt(1)
	v_mfma_f32_32x32x16_bf16 v[96:111], v[148:151], v[144:147], v[96:111]
	ds_read_b128 v[148:151], v204 offset:45056
	ds_read_b128 v[198:201], v204 offset:33024
	s_waitcnt lgkmcnt(1)
	v_mfma_f32_32x32x16_bf16 v[112:127], v[148:151], v[144:147], v[112:127]
	ds_read_b128 v[144:147], v193 offset:45184
	ds_read_b128 v[148:151], v193 offset:45312
	v_mfma_f32_32x32x16_bf16 v[96:111], v[194:197], v[140:143], v[96:111]
	s_waitcnt lgkmcnt(1)
	v_mfma_f32_32x32x16_bf16 v[112:127], v[144:147], v[140:143], v[112:127]
	ds_read_b128 v[140:143], v202 offset:45184
	ds_read_b128 v[144:147], v202 offset:45312
	v_mfma_f32_32x32x16_bf16 v[96:111], v[210:213], v[136:139], v[96:111]
	s_waitcnt lgkmcnt(1)
	v_mfma_f32_32x32x16_bf16 v[112:127], v[140:143], v[136:139], v[112:127]
	ds_read_b128 v[136:139], v203 offset:45184
	ds_read_b128 v[140:143], v203 offset:45312
	v_mfma_f32_32x32x16_bf16 v[96:111], v[156:159], v[132:135], v[96:111]
	v_exp_f32_e32 v158, v80
	v_exp_f32_e32 v159, v81
	v_cvt_pk_bf16_f32 v80, v64, v65
	v_cvt_pk_bf16_f32 v81, v66, v67
	s_nop 1
	v_permlane32_swap_b32_e32 v81, v83
	v_add_f32_e32 v64, 0, v64
	s_waitcnt lgkmcnt(1)
	v_mfma_f32_32x32x16_bf16 v[112:127], v[136:139], v[132:135], v[112:127]
	ds_read_b128 v[132:135], v204 offset:45184
	ds_read_b128 v[136:139], v204 offset:45312
	v_exp_f32_e32 v204, v82
	v_cvt_pk_bf16_f32 v82, v68, v69
	s_nop 1
	v_permlane32_swap_b32_e32 v80, v82
	v_add_f32_e32 v64, v65, v64
	v_add_f32_e32 v64, v66, v64
	v_mfma_f32_32x32x16_bf16 v[96:111], v[152:155], v[128:131], v[96:111]
	v_add_f32_e32 v64, v67, v64
	v_add_f32_e32 v64, v68, v64
	v_add_f32_e32 v64, v69, v64
	v_add_f32_e32 v64, v70, v64
	v_add_f32_e32 v64, v71, v64
	v_add_f32_e32 v64, v72, v64
	v_add_f32_e32 v64, v73, v64
	s_waitcnt lgkmcnt(1)
	v_mfma_f32_32x32x16_bf16 v[112:127], v[132:135], v[128:131], v[112:127]
	ds_read_b128 v[128:131], v192
	ds_read_b128 v[132:135], v192 offset:1024
	v_add_f32_e32 v64, v74, v64
	v_add_f32_e32 v64, v75, v64
	v_cvt_pk_bf16_f32 v89, v204, v222
	v_add_f32_e32 v64, v76, v64
	v_add_f32_e32 v64, v77, v64
	v_add_f32_e32 v64, v78, v64
	s_waitcnt lgkmcnt(1)
	v_mfma_f32_32x32x16_bf16 v[96:111], v[206:209], v[128:131], v[96:111]
	v_add_f32_e32 v64, v79, v64
	v_add_f32_e32 v64, v158, v64
	v_add_f32_e32 v64, v159, v64
	v_add_f32_e32 v64, v204, v64
	v_add_f32_e32 v64, v222, v64
	v_add_f32_e32 v64, v223, v64
	v_mfma_f32_32x32x16_bf16 v[112:127], v[148:151], v[128:131], v[112:127]
	s_waitcnt lgkmcnt(0)
	v_mfma_f32_32x32x16_bf16 v[96:111], v[214:217], v[132:135], v[96:111]
	v_mfma_f32_32x32x16_bf16 v[112:127], v[144:147], v[132:135], v[112:127]
	ds_read_b128 v[128:131], v192 offset:2048
	ds_read_b128 v[132:135], v192 offset:3072
	s_waitcnt lgkmcnt(1)
	v_mfma_f32_32x32x16_bf16 v[96:111], v[218:221], v[128:131], v[96:111]
	v_exp_f32_e32 v218, v85
	v_exp_f32_e32 v219, v86
	v_exp_f32_e32 v220, v87
	v_cvt_pk_bf16_f32 v85, v74, v75
	v_cvt_pk_bf16_f32 v86, v76, v77
	v_cvt_pk_bf16_f32 v87, v78, v79
	s_nop 0
	v_permlane32_swap_b32_e32 v84, v86
	v_mfma_f32_32x32x16_bf16 v[112:127], v[140:143], v[128:131], v[112:127]
	v_permlane32_swap_b32_e32 v85, v87
	v_exp_f32_e32 v221, v88
	v_cvt_pk_bf16_f32 v88, v158, v159
	v_cvt_pk_bf16_f32 v90, v223, v218
	v_cvt_pk_bf16_f32 v91, v219, v220
	s_nop 0
	v_permlane32_swap_b32_e32 v88, v90
	s_waitcnt lgkmcnt(0)
; __device__ __forceinline__ void partialSM(f32x16& p0, f32x16& p1, float& M, float& alpha) {
;   float pmax = p0[0];
; #pragma unroll
;   for (int r = 1; r < 16; ++r) pmax = fmaxf(pmax, p0[r]);
; #pragma unroll
;   for (int r = 0; r < 16; ++r) pmax = fmaxf(pmax, p1[r]);
;   { auto rr = __builtin_amdgcn_permlane32_swap(__float_as_uint(pmax), __float_as_uint(pmax), false, false);
;     pmax = fmaxf(__uint_as_float(rr[0]), __uint_as_float(rr[1])); }
;   const float mn = fmaxf(M, pmax);
;   alpha = __builtin_amdgcn_exp2f(M - mn); M = mn;
; #pragma unroll
;   for (int r = 0; r < 16; ++r) { p0[r] -= mn; p1[r] -= mn; }
; #pragma unroll
;   for (int r = 0; r < 16; ++r) p0[r] = __builtin_amdgcn_exp2f(p0[r]);
; }
; __device__ __forceinline__ void finishSM(f32x16& p0, f32x16& p1, float alpha, float& l_reg, bf16x8& pa0, bf16x8& pa1, bf16x8& pa2, bf16x8& pa3) {
; #pragma unroll
;   for (int r = 0; r < 16; ++r) p1[r] = __builtin_amdgcn_exp2f(p1[r]);
;   float ps = 0;
; #pragma unroll
;   for (int r = 0; r < 16; ++r) ps += p0[r];
; #pragma unroll
;   for (int r = 0; r < 16; ++r) ps += p1[r];
;   { auto rr = __builtin_amdgcn_permlane32_swap(__float_as_uint(ps), __float_as_uint(ps), false, false);
;     ps = __uint_as_float(rr[0]) + __uint_as_float(rr[1]); }
;   l_reg = l_reg * alpha + ps;
;     ...
;   PK4(p0, 0, pa0); PK4(p0, 8, pa1); PK4(p1, 0, pa2); PK4(p1, 8, pa3);
;     ...
; }
; __device__ __forceinline__ void qkt(f32x16& p0, f32x16& p1, const char* Ks, const bf16x8* qr, const char* qlds, const int* kb) {
;   p0 = f32x16{}; p1 = f32x16{};
; #pragma unroll
;   for (int d0 = 0; d0 < 12; ++d0) { const int off = kb[d0 & 3] + (d0 >> 2) * 128;
;     bf16x8 b0 = *reinterpret_cast<const bf16x8*>(Ks + off);
;     bf16x8 b1 = *reinterpret_cast<const bf16x8*>(Ks + off + 32 * 384);
;     bf16x8 q; if (d0 < 8) q = qr[d0]; else q = *reinterpret_cast<const bf16x8*>(qlds + (d0 - 8) * 1024);
;     p0 = __builtin_amdgcn_mfma_f32_32x32x16_bf16(b0, q, p0, 0, 0, 0);
;     p1 = __builtin_amdgcn_mfma_f32_32x32x16_bf16(b1, q, p1, 0, 0, 0); }
; }
; __device__ __forceinline__ int v_st(int k, int c) { const int kk = (k & ~0xC) | ((k & 4) << 1) | ((k & 8) >> 1); return ((kk >> 3) * 4 + (c >> 5)) * 512 + ((kk & 7) * 32 + (c & 31)) * 2; }
; __device__ __forceinline__ int v_rd_base(int lane) { return ((lane & 3) << 3) | (((lane >> 2) & 3) << 6) | (((lane >> 4) & 1) << 5) | (((lane >> 5) & 1) << 8); }
	v_mfma_f32_32x32x16_bf16 v[96:111], v[198:201], v[132:135], v[96:111]
	v_permlane32_swap_b32_e32 v89, v91
	v_cvt_pk_bf16_f32 v92, v221, v224
	s_nop 1
	v_permlane32_swap_b32_e32 v92, v94
	v_add_f32_e32 v64, v218, v64
	v_add_f32_e32 v64, v219, v64
	v_mfma_f32_32x32x16_bf16 v[112:127], v[136:139], v[132:135], v[112:127]
	ds_read_b64_tr_b16 v[130:131], v188 offset:2048
	ds_read_b64_tr_b16 v[132:133], v188 offset:6144
	ds_read_b64_tr_b16 v[134:135], v188 offset:10240
	ds_read_b64_tr_b16 v[136:137], v188 offset:14336
	ds_read_b64_tr_b16 v[128:129], v188
	ds_read_b64_tr_b16 v[138:139], v188 offset:512
	ds_read_b64_tr_b16 v[142:143], v188 offset:1024
	ds_read_b64_tr_b16 v[146:147], v188 offset:1536
	ds_read_b64_tr_b16 v[140:141], v188 offset:2560
	ds_read_b64_tr_b16 v[144:145], v188 offset:3072
	ds_read_b64_tr_b16 v[148:149], v188 offset:3584
	v_max_f32_e32 v66, v97, v97
	v_max_f32_e32 v67, v96, v96
	v_max_f32_e32 v66, v67, v66
	v_max3_f32 v66, v66, v98, v99
	v_max3_f32 v66, v66, v100, v101
	v_max3_f32 v66, v66, v102, v103
	s_waitcnt lgkmcnt(6)
	v_mfma_f32_32x32x16_bf16 v[0:15], v[80:83], v[128:131], v[0:15]
	ds_read_b64_tr_b16 v[130:131], v188 offset:4096
	ds_read_b64_tr_b16 v[150:151], v188 offset:4608
	ds_read_b64_tr_b16 v[154:155], v188 offset:5120
	ds_read_b64_tr_b16 v[192:193], v188 offset:5632
	ds_read_b64_tr_b16 v[152:153], v188 offset:6656
	ds_read_b64_tr_b16 v[156:157], v188 offset:7168
	ds_read_b64_tr_b16 v[194:195], v188 offset:7680
	v_max3_f32 v66, v66, v104, v105
	v_max3_f32 v66, v66, v106, v107
	v_max3_f32 v66, v66, v108, v109
	v_max3_f32 v66, v66, v110, v111
	v_max3_f32 v66, v66, v112, v113
	v_max3_f32 v66, v66, v114, v115
	s_waitcnt lgkmcnt(9)
	v_mfma_f32_32x32x16_bf16 v[48:63], v[80:83], v[138:141], v[48:63]
	v_max3_f32 v66, v66, v116, v117
	v_max3_f32 v66, v66, v118, v119
	v_max3_f32 v66, v66, v120, v121
	v_add_f32_e32 v64, v220, v64
	v_max3_f32 v66, v66, v122, v123
	v_add_f32_e32 v64, v221, v64
	v_max3_f32 v66, v66, v124, v125
	s_waitcnt lgkmcnt(8)
	v_mfma_f32_32x32x16_bf16 v[32:47], v[80:83], v[142:145], v[32:47]
	v_add_f32_e32 v64, v224, v64
	v_max3_f32 v66, v66, v126, v127
	v_add_f32_e32 v64, v225, v64
	v_mov_b32_e32 v67, v66
	v_add_f32_e32 v64, v226, v64
	s_nop 0
	v_permlane32_swap_b32_e32 v66, v67
	s_waitcnt lgkmcnt(7)
	v_mfma_f32_32x32x16_bf16 v[16:31], v[80:83], v[146:149], v[16:31]
	v_add_f32_e32 v64, v227, v64
	v_max3_f32 v67, v191, v66, v67
	v_add_f32_e32 v64, v228, v64
	v_sub_f32_e32 v66, v191, v67
	v_add_f32_e32 v64, v229, v64
	v_exp_f32_e32 v66, v66
	v_add_f32_e32 v64, v230, v64
	s_waitcnt lgkmcnt(6)
	v_mfma_f32_32x32x16_bf16 v[0:15], v[84:87], v[130:133], v[0:15]
	ds_read_b64_tr_b16 v[132:133], v188 offset:8192
	ds_read_b64_tr_b16 v[128:129], v188 offset:8704
	ds_read_b64_tr_b16 v[196:197], v188 offset:9216
	ds_read_b64_tr_b16 v[200:201], v188 offset:9728
	ds_read_b64_tr_b16 v[130:131], v188 offset:10752
	ds_read_b64_tr_b16 v[198:199], v188 offset:11264
	ds_read_b64_tr_b16 v[202:203], v188 offset:11776
	v_mov_b32_e32 v65, v64
	s_nop 1
	v_permlane32_swap_b32_e32 v64, v65
	s_waitcnt lgkmcnt(9)
	v_mfma_f32_32x32x16_bf16 v[48:63], v[84:87], v[150:153], v[48:63]
	s_waitcnt lgkmcnt(8)
	v_mfma_f32_32x32x16_bf16 v[32:47], v[84:87], v[154:157], v[32:47]
	s_waitcnt lgkmcnt(7)
	v_mfma_f32_32x32x16_bf16 v[16:31], v[84:87], v[192:195], v[16:31]
	s_waitcnt lgkmcnt(6)
	v_mfma_f32_32x32x16_bf16 v[0:15], v[88:91], v[132:135], v[0:15]
	ds_read_b64_tr_b16 v[134:135], v188 offset:12288
	ds_read_b64_tr_b16 v[206:207], v188 offset:12800
	ds_read_b64_tr_b16 v[210:211], v188 offset:13312
	ds_read_b64_tr_b16 v[214:215], v188 offset:13824
	ds_read_b64_tr_b16 v[208:209], v188 offset:14848
	ds_read_b64_tr_b16 v[212:213], v188 offset:15360
	ds_read_b64_tr_b16 v[216:217], v188 offset:15872
	s_waitcnt lgkmcnt(9)
	v_mfma_f32_32x32x16_bf16 v[48:63], v[88:91], v[128:131], v[48:63]
	s_waitcnt lgkmcnt(8)
	v_mfma_f32_32x32x16_bf16 v[32:47], v[88:91], v[196:199], v[32:47]
	s_waitcnt lgkmcnt(7)
	v_mfma_f32_32x32x16_bf16 v[16:31], v[88:91], v[200:203], v[16:31]
	s_waitcnt lgkmcnt(6)
	v_mfma_f32_32x32x16_bf16 v[0:15], v[92:95], v[134:137], v[0:15]
	s_waitcnt lgkmcnt(2)
	v_mfma_f32_32x32x16_bf16 v[48:63], v[92:95], v[206:209], v[48:63]
	s_waitcnt lgkmcnt(1)
	v_mfma_f32_32x32x16_bf16 v[32:47], v[92:95], v[210:213], v[32:47]
	s_waitcnt lgkmcnt(0)
	v_mfma_f32_32x32x16_bf16 v[16:31], v[92:95], v[214:217], v[16:31]
	s_waitcnt vmcnt(0)
	v_cmp_gt_f32_e32 vcc, 1.0, v66
	s_cbranch_vccz .LBB0_674
	s_and_saveexec_b64 s[10:11], s[4:5]
	ds_write_b32 v189, v66 offset:128
	s_or_b64 exec, exec, s[10:11]
	s_waitcnt lgkmcnt(0)
	v_add_u32_e32 v80, s1, v166
	ds_read_b128 v[68:71], v80 offset:224
	ds_read_b128 v[72:75], v80 offset:192
	ds_read_b128 v[76:79], v80 offset:160
	ds_read_b128 v[80:83], v80 offset:128
	s_waitcnt lgkmcnt(3)
	v_pk_mul_f32 v[12:13], v[12:13], v[68:69]
	s_waitcnt lgkmcnt(2)
	v_pk_mul_f32 v[8:9], v[8:9], v[72:73]
	s_waitcnt lgkmcnt(1)
	v_pk_mul_f32 v[4:5], v[4:5], v[76:77]
	v_pk_mul_f32 v[14:15], v[14:15], v[70:71]
	v_pk_mul_f32 v[10:11], v[10:11], v[74:75]
	v_pk_mul_f32 v[6:7], v[6:7], v[78:79]
	s_waitcnt lgkmcnt(0)
	v_pk_mul_f32 v[2:3], v[2:3], v[82:83]
	v_pk_mul_f32 v[0:1], v[0:1], v[80:81]
	v_pk_mul_f32 v[60:61], v[60:61], v[68:69]
	v_pk_mul_f32 v[56:57], v[56:57], v[72:73]
	v_pk_mul_f32 v[52:53], v[52:53], v[76:77]
	v_pk_mul_f32 v[62:63], v[62:63], v[70:71]
	v_pk_mul_f32 v[58:59], v[58:59], v[74:75]
	v_pk_mul_f32 v[54:55], v[54:55], v[78:79]
	v_pk_mul_f32 v[50:51], v[50:51], v[82:83]
	v_pk_mul_f32 v[48:49], v[48:49], v[80:81]
	v_pk_mul_f32 v[44:45], v[44:45], v[68:69]
	v_pk_mul_f32 v[40:41], v[40:41], v[72:73]
	v_pk_mul_f32 v[36:37], v[36:37], v[76:77]
	v_pk_mul_f32 v[46:47], v[46:47], v[70:71]
	v_pk_mul_f32 v[42:43], v[42:43], v[74:75]
	v_pk_mul_f32 v[38:39], v[38:39], v[78:79]
	v_pk_mul_f32 v[34:35], v[34:35], v[82:83]
	v_pk_mul_f32 v[32:33], v[32:33], v[80:81]
	v_pk_mul_f32 v[28:29], v[28:29], v[68:69]
	v_pk_mul_f32 v[24:25], v[24:25], v[72:73]
	v_pk_mul_f32 v[20:21], v[20:21], v[76:77]
	v_pk_mul_f32 v[30:31], v[30:31], v[70:71]
	v_pk_mul_f32 v[26:27], v[26:27], v[74:75]
	v_pk_mul_f32 v[22:23], v[22:23], v[78:79]
	v_pk_mul_f32 v[18:19], v[18:19], v[82:83]
	v_pk_mul_f32 v[16:17], v[16:17], v[80:81]
